# NSA phase: static s_setprio 1 for waves 0-3 instead of 4-7
# speedup vs baseline: 1.0070x; 1.0033x over previous
; #define LAS __attribute__((address_space(3)))
; DI int opaque_tid() { int t = threadIdx.x; asm volatile("" : "+v"(t)); return t; }
; DI void phase_nsa(const Params& P, unsigned char* smem) {
;     const int tid = opaque_tid(), lane = tid & 63, wave = __builtin_amdgcn_readfirstlane(tid >> 6);
;     LAS unsigned char* wl = (LAS unsigned char*)smem + wave * NSA_WAVE_LDS;
.LBB0_373:
	s_or_b64 exec, exec, s[2:3]
	v_mov_b32_e32 v146, v215
	v_readfirstlane_b32 s89, v215
	s_cmpk_ge_u32 s89, 0x100
	s_cbranch_scc1 .Lnsa_prio_done
	s_setprio 1
